# LRU pass-1 tile loop: the 16 conv-input loads of each 16-token block issued at its top (one round trip instead of sixteen)
# speedup vs baseline: 1.0266x; 1.0148x over previous
.LBB0_889:
	v_lshl_add_u64 v[70:71], v[68:69], 0, s[14:15]
	global_load_ushort v160, v[70:71], off
	v_add_co_u32_e32 v176, vcc, s62, v70
	s_nop 1
	v_addc_co_u32_e32 v177, vcc, 0, v71, vcc
	global_load_ushort v161, v[176:177], off offset:1536
	v_add_co_u32_e32 v176, vcc, s47, v70
	s_nop 1
	v_addc_co_u32_e32 v177, vcc, 0, v71, vcc
	global_load_ushort v162, v[176:177], off offset:3072
	v_add_co_u32_e32 v176, vcc, s67, v70
	s_nop 1
	v_addc_co_u32_e32 v177, vcc, 0, v71, vcc
	global_load_ushort v163, v[176:177], off offset:512
	v_add_co_u32_e32 v176, vcc, s69, v70
	s_nop 1
	v_addc_co_u32_e32 v177, vcc, 0, v71, vcc
	global_load_ushort v164, v[176:177], off offset:2048
	v_add_co_u32_e32 v176, vcc, s70, v70
	s_nop 1
	v_addc_co_u32_e32 v177, vcc, 0, v71, vcc
	global_load_ushort v165, v[176:177], off offset:3584
	v_add_co_u32_e32 v176, vcc, s63, v70
	s_nop 1
	v_addc_co_u32_e32 v177, vcc, 0, v71, vcc
	global_load_ushort v166, v[176:177], off offset:1024
	v_add_co_u32_e32 v176, vcc, s64, v70
	s_nop 1
	v_addc_co_u32_e32 v177, vcc, 0, v71, vcc
	global_load_ushort v167, v[176:177], off offset:2560
	v_add_co_u32_e32 v176, vcc, s71, v70
	s_nop 1
	v_addc_co_u32_e32 v177, vcc, 0, v71, vcc
	global_load_ushort v168, v[176:177], off
	v_add_co_u32_e32 v176, vcc, s72, v70
	s_nop 1
	v_addc_co_u32_e32 v177, vcc, 0, v71, vcc
	global_load_ushort v169, v[176:177], off offset:1536
	v_add_co_u32_e32 v176, vcc, s73, v70
	s_nop 1
	v_addc_co_u32_e32 v177, vcc, 0, v71, vcc
	global_load_ushort v170, v[176:177], off offset:3072
	v_add_co_u32_e32 v176, vcc, s74, v70
	s_nop 1
	v_addc_co_u32_e32 v177, vcc, 0, v71, vcc
	global_load_ushort v171, v[176:177], off offset:512
	v_add_co_u32_e32 v176, vcc, s75, v70
	s_nop 1
	v_addc_co_u32_e32 v177, vcc, 0, v71, vcc
	global_load_ushort v172, v[176:177], off offset:2048
	v_add_co_u32_e32 v176, vcc, s76, v70
	s_nop 1
	v_addc_co_u32_e32 v177, vcc, 0, v71, vcc
	global_load_ushort v173, v[176:177], off offset:3584
	v_add_co_u32_e32 v176, vcc, s77, v70
	s_nop 1
	v_addc_co_u32_e32 v177, vcc, 0, v71, vcc
	global_load_ushort v174, v[176:177], off offset:1024
	v_add_co_u32_e32 v176, vcc, s78, v70
	s_nop 1
	v_addc_co_u32_e32 v177, vcc, 0, v71, vcc
	global_load_ushort v175, v[176:177], off offset:2560
	s_waitcnt vmcnt(0)
	v_mov_b32_e32 v72, v160
	v_fma_f32 v117, v16, v126, v107
	v_fmac_f32_e32 v117, v104, v127
	v_fmac_f32_e32 v117, v105, v129
	v_fma_f32 v118, v16, v127, v107
	v_fmac_f32_e32 v118, v104, v129
	v_fma_f32 v119, v16, v129, v107
	s_waitcnt vmcnt(0) lgkmcnt(0)
	v_lshlrev_b32_e32 v74, 16, v72
	v_fmac_f32_e32 v117, v106, v74
	v_cvt_pk_bf16_f32 v72, v117, v17
	ds_write_b16 v111, v72
	v_add_co_u32_e32 v72, vcc, s62, v70
	v_fmac_f32_e32 v118, v105, v74
	s_nop 0
	v_addc_co_u32_e32 v73, vcc, 0, v71, vcc
	v_mov_b32_e32 v72, v161
	v_fmac_f32_e32 v119, v104, v74
	v_fma_f32 v120, v16, v74, v107
	s_waitcnt lgkmcnt(0)
	v_lshlrev_b32_e32 v75, 16, v72
	v_fmac_f32_e32 v118, v106, v75
	v_cvt_pk_bf16_f32 v72, v118, v17
	ds_write_b16 v111, v72 offset:144
	v_add_co_u32_e32 v72, vcc, s47, v70
	v_fmac_f32_e32 v119, v105, v75
	s_nop 0
	v_addc_co_u32_e32 v73, vcc, 0, v71, vcc
	v_mov_b32_e32 v72, v162
	v_fmac_f32_e32 v120, v104, v75
	v_fma_f32 v121, v16, v75, v107
	s_waitcnt lgkmcnt(0)
	v_lshlrev_b32_e32 v76, 16, v72
	v_fmac_f32_e32 v119, v106, v76
	v_cvt_pk_bf16_f32 v72, v119, v17
	ds_write_b16 v111, v72 offset:288
	v_add_co_u32_e32 v72, vcc, s67, v70
	v_fmac_f32_e32 v120, v105, v76
	s_nop 0
	v_addc_co_u32_e32 v73, vcc, 0, v71, vcc
	v_mov_b32_e32 v72, v163
	v_fmac_f32_e32 v121, v104, v76
	v_fma_f32 v122, v16, v76, v107
	s_waitcnt lgkmcnt(0)
	v_lshlrev_b32_e32 v77, 16, v72
	v_fmac_f32_e32 v120, v106, v77
	v_cvt_pk_bf16_f32 v72, v120, v17
	ds_write_b16 v111, v72 offset:432
	v_add_co_u32_e32 v72, vcc, s69, v70
	v_fmac_f32_e32 v121, v105, v77
	s_nop 0
	v_addc_co_u32_e32 v73, vcc, 0, v71, vcc
	v_mov_b32_e32 v72, v164
	v_fmac_f32_e32 v122, v104, v77
	v_fma_f32 v123, v16, v77, v107
	s_waitcnt lgkmcnt(0)
	v_lshlrev_b32_e32 v74, 16, v72
	v_fmac_f32_e32 v121, v106, v74
	v_cvt_pk_bf16_f32 v72, v121, v17
	ds_write_b16 v111, v72 offset:576
	v_add_co_u32_e32 v72, vcc, s70, v70
	v_fmac_f32_e32 v122, v105, v74
	s_nop 0
	v_addc_co_u32_e32 v73, vcc, 0, v71, vcc
	v_mov_b32_e32 v72, v165
	v_fmac_f32_e32 v123, v104, v74
	v_fma_f32 v124, v16, v74, v107
	s_waitcnt lgkmcnt(0)
	v_lshlrev_b32_e32 v75, 16, v72
	v_fmac_f32_e32 v122, v106, v75
	v_cvt_pk_bf16_f32 v72, v122, v17
	ds_write_b16 v111, v72 offset:720
	v_add_co_u32_e32 v72, vcc, s63, v70
	v_fmac_f32_e32 v123, v105, v75
	s_nop 0
	v_addc_co_u32_e32 v73, vcc, 0, v71, vcc
	v_mov_b32_e32 v72, v166
	v_fmac_f32_e32 v124, v104, v75
	v_fma_f32 v125, v16, v75, v107
	s_waitcnt lgkmcnt(0)
	v_lshlrev_b32_e32 v76, 16, v72
	v_fmac_f32_e32 v123, v106, v76
	v_cvt_pk_bf16_f32 v72, v123, v17
	ds_write_b16 v111, v72 offset:864
	v_add_co_u32_e32 v72, vcc, s64, v70
	v_fmac_f32_e32 v124, v105, v76
	s_nop 0
	v_addc_co_u32_e32 v73, vcc, 0, v71, vcc
	v_mov_b32_e32 v72, v167
	v_fmac_f32_e32 v125, v104, v76
	v_fma_f32 v128, v16, v76, v107
	s_waitcnt lgkmcnt(0)
	v_lshlrev_b32_e32 v77, 16, v72
	v_fmac_f32_e32 v124, v106, v77
	v_cvt_pk_bf16_f32 v72, v124, v17
	ds_write_b16 v111, v72 offset:1008
	v_add_co_u32_e32 v72, vcc, s71, v70
	v_fmac_f32_e32 v125, v105, v77
	s_nop 0
	v_addc_co_u32_e32 v73, vcc, 0, v71, vcc
	v_mov_b32_e32 v72, v168
	v_fmac_f32_e32 v128, v104, v77
	v_fma_f32 v130, v16, v77, v107
	s_waitcnt lgkmcnt(0)
	v_lshlrev_b32_e32 v74, 16, v72
	v_fmac_f32_e32 v125, v106, v74
	v_cvt_pk_bf16_f32 v72, v125, v17
	ds_write_b16 v111, v72 offset:1152
	v_add_co_u32_e32 v72, vcc, s72, v70
	v_fmac_f32_e32 v128, v105, v74
	s_nop 0
	v_addc_co_u32_e32 v73, vcc, 0, v71, vcc
	v_mov_b32_e32 v72, v169
	v_fmac_f32_e32 v130, v104, v74
	v_fma_f32 v131, v16, v74, v107
	s_waitcnt lgkmcnt(0)
	v_lshlrev_b32_e32 v75, 16, v72
	v_fmac_f32_e32 v128, v106, v75
	v_cvt_pk_bf16_f32 v72, v128, v17
	ds_write_b16 v111, v72 offset:1296
	v_add_co_u32_e32 v72, vcc, s73, v70
	v_fmac_f32_e32 v130, v105, v75
	s_nop 0
	v_addc_co_u32_e32 v73, vcc, 0, v71, vcc
	v_mov_b32_e32 v72, v170
	v_fmac_f32_e32 v131, v104, v75
	v_fma_f32 v132, v16, v75, v107
	s_waitcnt lgkmcnt(0)
	v_lshlrev_b32_e32 v76, 16, v72
	v_fmac_f32_e32 v130, v106, v76
	v_cvt_pk_bf16_f32 v72, v130, v17
	ds_write_b16 v111, v72 offset:1440
	v_add_co_u32_e32 v72, vcc, s74, v70
	v_fmac_f32_e32 v131, v105, v76
	s_nop 0
	v_addc_co_u32_e32 v73, vcc, 0, v71, vcc
	v_mov_b32_e32 v72, v171
	v_fmac_f32_e32 v132, v104, v76
	v_fma_f32 v133, v16, v76, v107
	s_waitcnt lgkmcnt(0)
	v_lshlrev_b32_e32 v77, 16, v72
	v_fmac_f32_e32 v131, v106, v77
	v_cvt_pk_bf16_f32 v72, v131, v17
	ds_write_b16 v111, v72 offset:1584
	v_add_co_u32_e32 v72, vcc, s75, v70
	v_fmac_f32_e32 v132, v105, v77
	s_nop 0
	v_addc_co_u32_e32 v73, vcc, 0, v71, vcc
	v_mov_b32_e32 v72, v172
	v_fmac_f32_e32 v133, v104, v77
	v_fma_f32 v134, v16, v77, v107
	s_waitcnt lgkmcnt(0)
	v_lshlrev_b32_e32 v74, 16, v72
	v_fmac_f32_e32 v132, v106, v74
	v_cvt_pk_bf16_f32 v72, v132, v17
	ds_write_b16 v111, v72 offset:1728
	v_add_co_u32_e32 v72, vcc, s76, v70
	v_fmac_f32_e32 v133, v105, v74
	s_nop 0
	v_addc_co_u32_e32 v73, vcc, 0, v71, vcc
	v_mov_b32_e32 v72, v173
	v_fmac_f32_e32 v134, v104, v74
	s_waitcnt lgkmcnt(0)
	v_lshlrev_b32_e32 v126, 16, v72
	v_fmac_f32_e32 v133, v106, v126
	v_cvt_pk_bf16_f32 v72, v133, v17
	ds_write_b16 v111, v72 offset:1872
	v_add_co_u32_e32 v72, vcc, s77, v70
	v_fmac_f32_e32 v134, v105, v126
	s_nop 0
	v_addc_co_u32_e32 v73, vcc, 0, v71, vcc
	v_mov_b32_e32 v72, v174
	v_add_co_u32_e32 v70, vcc, s78, v70
	s_waitcnt lgkmcnt(0)
	v_lshlrev_b32_e32 v127, 16, v72
	v_fmac_f32_e32 v134, v106, v127
	v_cvt_pk_bf16_f32 v72, v134, v17
	ds_write_b16 v111, v72 offset:2016
	v_addc_co_u32_e32 v71, vcc, 0, v71, vcc
	v_mov_b32_e32 v70, v175
	v_fma_f32 v71, v16, v74, v107
	v_fmac_f32_e32 v71, v104, v126
	v_fmac_f32_e32 v71, v105, v127
	s_waitcnt lgkmcnt(0)
	v_lshlrev_b32_e32 v129, 16, v70
	v_fmac_f32_e32 v71, v106, v129
	v_cvt_pk_bf16_f32 v70, v71, v17
	ds_write_b16 v111, v70 offset:2160
	s_waitcnt lgkmcnt(0)
	s_barrier
	ds_read_b128 v[72:75], v114
	ds_read_b128 v[136:139], v114 offset:64
	s_waitcnt lgkmcnt(1)
	v_mfma_f32_16x16x32_bf16 v[76:79], v[0:3], v[72:75], 0
	v_add_u32_e32 v70, 0x900, v115
	v_mfma_f32_16x16x32_bf16 v[80:83], v[8:11], v[72:75], 0
	v_mfma_f32_16x16x32_bf16 v[84:87], v[18:21], v[72:75], 0
	s_waitcnt lgkmcnt(0)
	v_mfma_f32_16x16x32_bf16 v[76:79], v[4:7], v[136:139], v[76:79]
	v_mfma_f32_16x16x32_bf16 v[88:91], v[26:29], v[72:75], 0
	v_mfma_f32_16x16x32_bf16 v[80:83], v[12:15], v[136:139], v[80:83]
	s_nop 5
	ds_write2_b32 v70, v76, v77 offset1:1
	v_add_u32_e32 v70, 0x908, v115
	ds_write2_b32 v70, v78, v79 offset1:1
	v_mfma_f32_16x16x32_bf16 v[92:95], v[34:37], v[72:75], 0
	v_add_u32_e32 v70, 0x940, v115
	ds_write2_b32 v70, v80, v81 offset1:1
	v_add_u32_e32 v70, 0x948, v115
	v_mfma_f32_16x16x32_bf16 v[84:87], v[22:25], v[136:139], v[84:87]
	ds_write2_b32 v70, v82, v83 offset1:1
	v_add_u32_e32 v70, 0x980, v115
	v_mfma_f32_16x16x32_bf16 v[96:99], v[42:45], v[72:75], 0
	v_mfma_f32_16x16x32_bf16 v[88:91], v[30:33], v[136:139], v[88:91]
	s_nop 3
	ds_write2_b32 v70, v84, v85 offset1:1
	v_add_u32_e32 v70, 0x988, v115
	ds_write2_b32 v70, v86, v87 offset1:1
	v_mfma_f32_16x16x32_bf16 v[100:103], v[50:53], v[72:75], 0
	v_add_u32_e32 v70, 0x9c0, v115
	ds_write2_b32 v70, v88, v89 offset1:1
	v_add_u32_e32 v70, 0x9c8, v115
	v_mfma_f32_16x16x32_bf16 v[92:95], v[38:41], v[136:139], v[92:95]
	ds_write2_b32 v70, v90, v91 offset1:1
	v_add_u32_e32 v70, 0xa00, v115
	v_mfma_f32_16x16x32_bf16 v[72:75], v[58:61], v[72:75], 0
	v_mfma_f32_16x16x32_bf16 v[96:99], v[46:49], v[136:139], v[96:99]
	s_nop 3
	ds_write2_b32 v70, v92, v93 offset1:1
	v_add_u32_e32 v70, 0xa08, v115
	ds_write2_b32 v70, v94, v95 offset1:1
	v_mfma_f32_16x16x32_bf16 v[100:103], v[54:57], v[136:139], v[100:103]
	v_add_u32_e32 v70, 0xa40, v115
	ds_write2_b32 v70, v96, v97 offset1:1
	v_add_u32_e32 v70, 0xa48, v115
	v_mfma_f32_16x16x32_bf16 v[72:75], v[62:65], v[136:139], v[72:75]
	ds_write2_b32 v70, v98, v99 offset1:1
	v_add_u32_e32 v70, 0xa80, v115
	s_nop 1
	ds_write2_b32 v70, v100, v101 offset1:1
	v_add_u32_e32 v70, 0xa88, v115
	ds_write2_b32 v70, v102, v103 offset1:1
	v_add_u32_e32 v70, 0xac0, v115
	ds_write2_b32 v70, v72, v73 offset1:1
	v_add_u32_e32 v70, 0xac8, v115
	ds_write2_b32 v70, v74, v75 offset1:1
	s_waitcnt lgkmcnt(0)
	s_barrier
	ds_read2st64_b32 v[72:73], v113 offset0:9 offset1:10
	s_waitcnt lgkmcnt(0)
	v_add_f32_e32 v70, v108, v72
	v_mul_f32_e32 v70, 0xbfb8aa3b, v70
	v_exp_f32_e32 v70, v70
	s_nop 0
	v_add_f32_e32 v70, 1.0, v70
	v_rcp_f32_e32 v70, v70
	s_nop 0
	v_mul_f32_e32 v72, v112, v70
	v_mul_f32_e32 v70, 0x3fb8aa3b, v72
	v_exp_f32_e32 v70, v70
	v_add_f32_e32 v72, v72, v72
	v_cmp_nlt_f32_e32 vcc, s80, v72
	s_and_saveexec_b64 s[16:17], vcc
	s_xor_b64 s[16:17], exec, s[16:17]
	v_fma_f32 v135, -v70, v70, 1.0
	s_andn2_saveexec_b64 s[16:17], s[16:17]
	v_fmamk_f32 v74, v72, 0x3d2aaaab, v233
	v_fma_f32 v74, v72, v74, 0.5
	v_fma_f32 v74, v72, v74, 1.0
	v_mul_f32_e64 v135, v74, -v72
	s_or_b64 exec, exec, s[16:17]
	v_add_u32_e32 v72, 4, v113
	ds_read2st64_b32 v[74:75], v72 offset0:11 offset1:12
	s_waitcnt lgkmcnt(0)
	v_add_f32_e32 v72, v108, v74
	v_mul_f32_e32 v72, 0xbfb8aa3b, v72
	v_exp_f32_e32 v72, v72
	s_nop 0
	v_add_f32_e32 v72, 1.0, v72
	v_rcp_f32_e32 v72, v72
	s_nop 0
	v_mul_f32_e32 v72, v112, v72
	v_mul_f32_e32 v74, 0x3fb8aa3b, v72
	v_exp_f32_e32 v74, v74
	v_add_f32_e32 v72, v72, v72
	v_cmp_nlt_f32_e32 vcc, s80, v72
	s_and_saveexec_b64 s[16:17], vcc
	s_xor_b64 s[16:17], exec, s[16:17]
	v_fma_f32 v136, -v74, v74, 1.0
	s_andn2_saveexec_b64 s[16:17], s[16:17]
	v_fmamk_f32 v76, v72, 0x3d2aaaab, v233
	v_fma_f32 v76, v72, v76, 0.5
	v_fma_f32 v76, v72, v76, 1.0
	v_mul_f32_e64 v136, v76, -v72
	s_or_b64 exec, exec, s[16:17]
	v_add_u32_e32 v72, 8, v113
	ds_read2st64_b32 v[76:77], v72 offset0:13 offset1:14
	s_waitcnt lgkmcnt(0)
	v_add_f32_e32 v72, v108, v76
	v_mul_f32_e32 v72, 0xbfb8aa3b, v72
	v_exp_f32_e32 v72, v72
	s_nop 0
	v_add_f32_e32 v72, 1.0, v72
	v_rcp_f32_e32 v72, v72
	s_nop 0
	v_mul_f32_e32 v72, v112, v72
	v_mul_f32_e32 v76, 0x3fb8aa3b, v72
	v_exp_f32_e32 v76, v76
	v_add_f32_e32 v72, v72, v72
	v_cmp_nlt_f32_e32 vcc, s80, v72
	s_and_saveexec_b64 s[16:17], vcc
	s_xor_b64 s[16:17], exec, s[16:17]
	v_fma_f32 v137, -v76, v76, 1.0
	s_andn2_saveexec_b64 s[16:17], s[16:17]
	v_fmamk_f32 v78, v72, 0x3d2aaaab, v233
	v_fma_f32 v78, v72, v78, 0.5
	v_fma_f32 v78, v72, v78, 1.0
	v_mul_f32_e64 v137, v78, -v72
	s_or_b64 exec, exec, s[16:17]
	v_add_u32_e32 v72, 12, v113
	ds_read2st64_b32 v[78:79], v72 offset0:15 offset1:16
	s_waitcnt lgkmcnt(0)
	v_add_f32_e32 v72, v108, v78
	v_mul_f32_e32 v72, 0xbfb8aa3b, v72
	v_exp_f32_e32 v72, v72
	s_nop 0
	v_add_f32_e32 v72, 1.0, v72
	v_rcp_f32_e32 v72, v72
	s_nop 0
	v_mul_f32_e32 v72, v112, v72
	v_mul_f32_e32 v78, 0x3fb8aa3b, v72
	v_exp_f32_e32 v78, v78
	v_add_f32_e32 v72, v72, v72
	v_cmp_nlt_f32_e32 vcc, s80, v72
	s_and_saveexec_b64 s[16:17], vcc
	s_xor_b64 s[16:17], exec, s[16:17]
	v_fma_f32 v138, -v78, v78, 1.0
	s_andn2_saveexec_b64 s[16:17], s[16:17]
	v_fmamk_f32 v80, v72, 0x3d2aaaab, v233
	v_fma_f32 v80, v72, v80, 0.5
	v_fma_f32 v80, v72, v80, 1.0
	v_mul_f32_e64 v138, v80, -v72
	s_or_b64 exec, exec, s[16:17]
	v_add_u32_e32 v72, 16, v113
	ds_read2st64_b32 v[80:81], v72 offset0:17 offset1:18
	s_waitcnt lgkmcnt(0)
	v_add_f32_e32 v72, v108, v80
	v_mul_f32_e32 v72, 0xbfb8aa3b, v72
	v_exp_f32_e32 v72, v72
	s_nop 0
	v_add_f32_e32 v72, 1.0, v72
	v_rcp_f32_e32 v72, v72
	s_nop 0
	v_mul_f32_e32 v72, v112, v72
	v_mul_f32_e32 v80, 0x3fb8aa3b, v72
	v_exp_f32_e32 v80, v80
	v_add_f32_e32 v72, v72, v72
	v_cmp_nlt_f32_e32 vcc, s80, v72
	s_and_saveexec_b64 s[16:17], vcc
	s_xor_b64 s[16:17], exec, s[16:17]
	v_fma_f32 v139, -v80, v80, 1.0
	s_andn2_saveexec_b64 s[16:17], s[16:17]
	v_fmamk_f32 v82, v72, 0x3d2aaaab, v233
	v_fma_f32 v82, v72, v82, 0.5
	v_fma_f32 v82, v72, v82, 1.0
	v_mul_f32_e64 v139, v82, -v72
	s_or_b64 exec, exec, s[16:17]
	v_add_u32_e32 v72, 20, v113
	ds_read2st64_b32 v[82:83], v72 offset0:19 offset1:20
	s_waitcnt lgkmcnt(0)
	v_add_f32_e32 v72, v108, v82
	v_mul_f32_e32 v72, 0xbfb8aa3b, v72
	v_exp_f32_e32 v72, v72
	s_nop 0
	v_add_f32_e32 v72, 1.0, v72
	v_rcp_f32_e32 v72, v72
	s_nop 0
	v_mul_f32_e32 v72, v112, v72
	v_mul_f32_e32 v82, 0x3fb8aa3b, v72
	v_exp_f32_e32 v82, v82
	v_add_f32_e32 v72, v72, v72
	v_cmp_nlt_f32_e32 vcc, s80, v72
	s_and_saveexec_b64 s[16:17], vcc
	s_xor_b64 s[16:17], exec, s[16:17]
	v_fma_f32 v140, -v82, v82, 1.0
	s_andn2_saveexec_b64 s[16:17], s[16:17]
	v_fmamk_f32 v84, v72, 0x3d2aaaab, v233
	v_fma_f32 v84, v72, v84, 0.5
	v_fma_f32 v84, v72, v84, 1.0
	v_mul_f32_e64 v140, v84, -v72
	s_or_b64 exec, exec, s[16:17]
	v_add_u32_e32 v72, 24, v113
	ds_read2st64_b32 v[84:85], v72 offset0:21 offset1:22
	s_waitcnt lgkmcnt(0)
	v_add_f32_e32 v72, v108, v84
	v_mul_f32_e32 v72, 0xbfb8aa3b, v72
	v_exp_f32_e32 v72, v72
	s_nop 0
	v_add_f32_e32 v72, 1.0, v72
	v_rcp_f32_e32 v72, v72
	s_nop 0
	v_mul_f32_e32 v72, v112, v72
	v_mul_f32_e32 v84, 0x3fb8aa3b, v72
	v_exp_f32_e32 v84, v84
	v_add_f32_e32 v72, v72, v72
	v_cmp_nlt_f32_e32 vcc, s80, v72
	s_and_saveexec_b64 s[16:17], vcc
	s_xor_b64 s[16:17], exec, s[16:17]
	v_fma_f32 v141, -v84, v84, 1.0
	s_andn2_saveexec_b64 s[16:17], s[16:17]
	v_fmamk_f32 v86, v72, 0x3d2aaaab, v233
	v_fma_f32 v86, v72, v86, 0.5
	v_fma_f32 v86, v72, v86, 1.0
	v_mul_f32_e64 v141, v86, -v72
	s_or_b64 exec, exec, s[16:17]
	v_add_u32_e32 v72, 28, v113
	ds_read2st64_b32 v[86:87], v72 offset0:23 offset1:24
	s_waitcnt lgkmcnt(0)
	v_add_f32_e32 v72, v108, v86
	v_mul_f32_e32 v72, 0xbfb8aa3b, v72
	v_exp_f32_e32 v72, v72
	s_nop 0
	v_add_f32_e32 v72, 1.0, v72
	v_rcp_f32_e32 v72, v72
	s_nop 0
	v_mul_f32_e32 v72, v112, v72
	v_mul_f32_e32 v86, 0x3fb8aa3b, v72
	v_exp_f32_e32 v86, v86
	v_add_f32_e32 v72, v72, v72
	v_cmp_nlt_f32_e32 vcc, s80, v72
	s_and_saveexec_b64 s[16:17], vcc
	s_xor_b64 s[16:17], exec, s[16:17]
	v_fma_f32 v142, -v86, v86, 1.0
	s_andn2_saveexec_b64 s[16:17], s[16:17]
	v_fmamk_f32 v88, v72, 0x3d2aaaab, v233
	v_fma_f32 v88, v72, v88, 0.5
	v_fma_f32 v88, v72, v88, 1.0
	v_mul_f32_e64 v142, v88, -v72
	s_or_b64 exec, exec, s[16:17]
	v_add_u32_e32 v72, 32, v113
	ds_read2st64_b32 v[88:89], v72 offset0:25 offset1:26
	s_waitcnt lgkmcnt(0)
	v_add_f32_e32 v72, v108, v88
	v_mul_f32_e32 v72, 0xbfb8aa3b, v72
	v_exp_f32_e32 v72, v72
	s_nop 0
	v_add_f32_e32 v72, 1.0, v72
	v_rcp_f32_e32 v72, v72
	s_nop 0
	v_mul_f32_e32 v72, v112, v72
	v_mul_f32_e32 v88, 0x3fb8aa3b, v72
	v_exp_f32_e32 v88, v88
	v_add_f32_e32 v72, v72, v72
	v_cmp_nlt_f32_e32 vcc, s80, v72
	s_and_saveexec_b64 s[16:17], vcc
	s_xor_b64 s[16:17], exec, s[16:17]
	v_fma_f32 v143, -v88, v88, 1.0
	s_andn2_saveexec_b64 s[16:17], s[16:17]
	v_fmamk_f32 v90, v72, 0x3d2aaaab, v233
	v_fma_f32 v90, v72, v90, 0.5
	v_fma_f32 v90, v72, v90, 1.0
	v_mul_f32_e64 v143, v90, -v72
	s_or_b64 exec, exec, s[16:17]
	v_add_u32_e32 v72, 36, v113
	ds_read2st64_b32 v[90:91], v72 offset0:27 offset1:28
	s_waitcnt lgkmcnt(0)
	v_add_f32_e32 v72, v108, v90
	v_mul_f32_e32 v72, 0xbfb8aa3b, v72
	v_exp_f32_e32 v72, v72
	s_nop 0
	v_add_f32_e32 v72, 1.0, v72
	v_rcp_f32_e32 v72, v72
	s_nop 0
	v_mul_f32_e32 v72, v112, v72
	v_mul_f32_e32 v90, 0x3fb8aa3b, v72
	v_exp_f32_e32 v90, v90
	v_add_f32_e32 v72, v72, v72
	v_cmp_nlt_f32_e32 vcc, s80, v72
	s_and_saveexec_b64 s[16:17], vcc
	s_xor_b64 s[16:17], exec, s[16:17]
	v_fma_f32 v144, -v90, v90, 1.0
	s_andn2_saveexec_b64 s[16:17], s[16:17]
	v_fmamk_f32 v92, v72, 0x3d2aaaab, v233
	v_fma_f32 v92, v72, v92, 0.5
	v_fma_f32 v92, v72, v92, 1.0
	v_mul_f32_e64 v144, v92, -v72
	s_or_b64 exec, exec, s[16:17]
	v_add_u32_e32 v72, 40, v113
	ds_read2st64_b32 v[92:93], v72 offset0:29 offset1:30
	s_waitcnt lgkmcnt(0)
	v_add_f32_e32 v72, v108, v92
	v_mul_f32_e32 v72, 0xbfb8aa3b, v72
	v_exp_f32_e32 v72, v72
	s_nop 0
	v_add_f32_e32 v72, 1.0, v72
	v_rcp_f32_e32 v72, v72
	s_nop 0
	v_mul_f32_e32 v72, v112, v72
	v_mul_f32_e32 v92, 0x3fb8aa3b, v72
	v_exp_f32_e32 v92, v92
	v_add_f32_e32 v72, v72, v72
	v_cmp_nlt_f32_e32 vcc, s80, v72
	s_and_saveexec_b64 s[16:17], vcc
	s_xor_b64 s[16:17], exec, s[16:17]
	v_fma_f32 v145, -v92, v92, 1.0
	s_andn2_saveexec_b64 s[16:17], s[16:17]
	v_fmamk_f32 v94, v72, 0x3d2aaaab, v233
	v_fma_f32 v94, v72, v94, 0.5
	v_fma_f32 v94, v72, v94, 1.0
	v_mul_f32_e64 v145, v94, -v72
	s_or_b64 exec, exec, s[16:17]
	v_add_u32_e32 v72, 44, v113
	ds_read2st64_b32 v[94:95], v72 offset0:31 offset1:32
	s_waitcnt lgkmcnt(0)
	v_add_f32_e32 v72, v108, v94
	v_mul_f32_e32 v72, 0xbfb8aa3b, v72
	v_exp_f32_e32 v72, v72
	s_nop 0
	v_add_f32_e32 v72, 1.0, v72
	v_rcp_f32_e32 v72, v72
	s_nop 0
	v_mul_f32_e32 v72, v112, v72
	v_mul_f32_e32 v94, 0x3fb8aa3b, v72
	v_exp_f32_e32 v94, v94
	v_add_f32_e32 v72, v72, v72
	v_cmp_nlt_f32_e32 vcc, s80, v72
	s_and_saveexec_b64 s[16:17], vcc
	s_xor_b64 s[16:17], exec, s[16:17]
	v_fma_f32 v146, -v94, v94, 1.0
	s_andn2_saveexec_b64 s[16:17], s[16:17]
	v_fmamk_f32 v96, v72, 0x3d2aaaab, v233
	v_fma_f32 v96, v72, v96, 0.5
	v_fma_f32 v96, v72, v96, 1.0
	v_mul_f32_e64 v146, v96, -v72
	s_or_b64 exec, exec, s[16:17]
	v_add_u32_e32 v72, 48, v113
	ds_read2st64_b32 v[96:97], v72 offset0:33 offset1:34
	s_waitcnt lgkmcnt(0)
	v_add_f32_e32 v72, v108, v96
	v_mul_f32_e32 v72, 0xbfb8aa3b, v72
	v_exp_f32_e32 v72, v72
	s_nop 0
	v_add_f32_e32 v72, 1.0, v72
	v_rcp_f32_e32 v72, v72
	s_nop 0
	v_mul_f32_e32 v72, v112, v72
	v_mul_f32_e32 v96, 0x3fb8aa3b, v72
	v_exp_f32_e32 v96, v96
	v_add_f32_e32 v72, v72, v72
	v_cmp_nlt_f32_e32 vcc, s80, v72
	s_and_saveexec_b64 s[16:17], vcc
	s_xor_b64 s[16:17], exec, s[16:17]
	v_fma_f32 v147, -v96, v96, 1.0
	s_andn2_saveexec_b64 s[16:17], s[16:17]
	v_fmamk_f32 v98, v72, 0x3d2aaaab, v233
	v_fma_f32 v98, v72, v98, 0.5
	v_fma_f32 v98, v72, v98, 1.0
	v_mul_f32_e64 v147, v98, -v72
	s_or_b64 exec, exec, s[16:17]
	v_add_u32_e32 v72, 52, v113
	ds_read2st64_b32 v[98:99], v72 offset0:35 offset1:36
	s_waitcnt lgkmcnt(0)
	v_add_f32_e32 v72, v108, v98
	v_mul_f32_e32 v72, 0xbfb8aa3b, v72
	v_exp_f32_e32 v72, v72
	s_nop 0
	v_add_f32_e32 v72, 1.0, v72
	v_rcp_f32_e32 v72, v72
	s_nop 0
	v_mul_f32_e32 v72, v112, v72
	v_mul_f32_e32 v98, 0x3fb8aa3b, v72
	v_exp_f32_e32 v98, v98
	v_add_f32_e32 v72, v72, v72
	v_cmp_nlt_f32_e32 vcc, s80, v72
	s_and_saveexec_b64 s[16:17], vcc
	s_xor_b64 s[16:17], exec, s[16:17]
	v_fma_f32 v148, -v98, v98, 1.0
	s_andn2_saveexec_b64 s[16:17], s[16:17]
	v_fmamk_f32 v100, v72, 0x3d2aaaab, v233
	v_fma_f32 v100, v72, v100, 0.5
	v_fma_f32 v100, v72, v100, 1.0
	v_mul_f32_e64 v148, v100, -v72
	s_or_b64 exec, exec, s[16:17]
	v_add_u32_e32 v72, 56, v113
	ds_read2st64_b32 v[100:101], v72 offset0:37 offset1:38
	s_waitcnt lgkmcnt(0)
	v_add_f32_e32 v72, v108, v100
	v_mul_f32_e32 v72, 0xbfb8aa3b, v72
	v_exp_f32_e32 v72, v72
	s_nop 0
	v_add_f32_e32 v72, 1.0, v72
	v_rcp_f32_e32 v72, v72
	s_nop 0
	v_mul_f32_e32 v72, v112, v72
	v_mul_f32_e32 v100, 0x3fb8aa3b, v72
	v_exp_f32_e32 v100, v100
	v_add_f32_e32 v72, v72, v72
	v_cmp_nlt_f32_e32 vcc, s80, v72
	s_and_saveexec_b64 s[16:17], vcc
	s_xor_b64 s[16:17], exec, s[16:17]
	v_fma_f32 v149, -v100, v100, 1.0
	s_andn2_saveexec_b64 s[16:17], s[16:17]
	v_fmamk_f32 v102, v72, 0x3d2aaaab, v233
	v_fma_f32 v102, v72, v102, 0.5
	v_fma_f32 v102, v72, v102, 1.0
	v_mul_f32_e64 v149, v102, -v72
	s_or_b64 exec, exec, s[16:17]
	v_add_u32_e32 v72, 60, v113
	ds_read2st64_b32 v[102:103], v72 offset0:39 offset1:40
	s_waitcnt lgkmcnt(0)
	v_add_f32_e32 v72, v108, v102
	v_mul_f32_e32 v72, 0xbfb8aa3b, v72
	v_exp_f32_e32 v72, v72
	s_nop 0
	v_add_f32_e32 v72, 1.0, v72
	v_rcp_f32_e32 v72, v72
	s_nop 0
	v_mul_f32_e32 v102, v112, v72
	v_mul_f32_e32 v72, 0x3fb8aa3b, v102
	v_exp_f32_e32 v72, v72
	v_add_f32_e32 v150, v102, v102
	v_cmp_nlt_f32_e32 vcc, s80, v150
	s_and_saveexec_b64 s[16:17], vcc
	s_xor_b64 s[16:17], exec, s[16:17]
	v_fma_f32 v102, -v72, v72, 1.0
	s_andn2_saveexec_b64 s[16:17], s[16:17]
	s_cbranch_execz .LBB0_888
	v_fmamk_f32 v102, v150, 0x3d2aaaab, v233
	v_fma_f32 v102, v150, v102, 0.5
	v_fma_f32 v102, v150, v102, 1.0
	v_mul_f32_e64 v102, v102, -v150
	s_branch .LBB0_888
